# grid-barrier poll back-off: s_sleep 8 instead of 2 in the 4 counter-barrier poll loops
# speedup vs baseline: 1.0011x; 1.0011x over previous
; __global__ void __launch_bounds__(512, 2) fwd_megakernel(Params p) {
;     ...
;     grid.sync();
.Lmy_gs0_poll:
	s_sleep 8
	global_load_dword v0, v2, s[0:1] sc1
	s_waitcnt vmcnt(0)
	v_readfirstlane_b32 vcc_lo, v0
	s_nop 1
	s_cmp_lt_u32 vcc_lo, 0x100
	s_cbranch_scc1 .Lmy_gs0_poll
	buffer_inv sc1
	s_waitcnt vmcnt(0)
